# attention ping-pong: waves 0-3 run PV(t-1),QK(t),softmax(t); waves 4-7 run softmax(t-1),PV(t-1),QK(t); K staged one tile ahead of V
# speedup vs baseline: 1.0076x; 1.0076x over previous
; #define GAS __attribute__((address_space(1)))
; #define LAS __attribute__((address_space(3)))
; DI void u_attn2(Frame& F, int h, int qb, int sp, int ntile) {
;     ...
;     unsigned char* ws = F.ws; const int tid = tid_, lane = tid & 63, w = F.wave, g4 = lane >> 4, lc = lane & 15;
;     LAS bf16* Ks = (LAS bf16*)F.lds; LAS bf16* Vs = Ks + 64 * 200;
;     const bf16* QM = (const bf16*)(ws + WS_QM); const bf16* KM = (const bf16*)(ws + WS_KM) + h * 192; const bf16* VT = (const bf16*)(ws + WS_VT) + (size_t)(h * 128) * S;
;     const int q0 = qb * 256 + w * 32, cw = 4 * qb + (w >> 1);
;     bf16x8 qf[2][6];
; #pragma unroll
;     for (int qq = 0; qq < 2; ++qq)
; #pragma unroll
;         for (int ks = 0; ks < 6; ++ks) qf[qq][ks] = *(const GAS bf16x8*)(QM + (size_t)(q0 + qq * 16 + lc) * 768 + h * 192 + ks * 32 + g4 * 8);
;     f32x4 o[8][2]; float mrun[2], lrun[2];
; #pragma unroll
;     for (int db = 0; db < 8; ++db)
; #pragma unroll
;         for (int qq = 0; qq < 2; ++qq) o[db][qq] = (f32x4){0.f, 0.f, 0.f, 0.f};
;     mrun[0] = mrun[1] = -1e30f; lrun[0] = lrun[1] = 0.f;
;     u32x4 kreg[3], vreg[2];
;     const int kt0 = 16 * sp;
;     ...
;     AT_LOAD(kt0)
.LBB0_2232:
	s_bitcmp0_b32 s44, 0
	s_cselect_b32 s31, s9, s41
	s_add_i32 s30, s31, s30
	s_cmpk_gt_i32 s30, 0x23f
	s_cbranch_scc1 .LBB0_2231
	s_ashr_i32 s31, s30, 31
	s_lshl_b64 s[30:31], s[30:31], 2
	s_add_u32 s30, s25, s30
	s_addc_u32 s31, s40, s31
	v_mov_b64_e32 v[2:3], s[30:31]
	flat_load_dword v138, v[2:3]
	v_mov_b32_e32 v158, v159
	v_mov_b32_e32 v20, v19
	v_mov_b32_e32 v21, v19
	v_mov_b32_e32 v18, v19
	v_mov_b64_e32 v[64:65], v[20:21]
	v_mov_b64_e32 v[56:57], v[20:21]
	v_mov_b64_e32 v[60:61], v[20:21]
	v_mov_b64_e32 v[68:69], v[20:21]
	v_mov_b64_e32 v[136:137], v[20:21]
	v_mov_b64_e32 v[120:121], v[20:21]
	v_mov_b64_e32 v[108:109], v[20:21]
	v_mov_b64_e32 v[104:105], v[20:21]
	v_mov_b64_e32 v[100:101], v[20:21]
	v_mov_b64_e32 v[96:97], v[20:21]
	v_mov_b64_e32 v[92:93], v[20:21]
	v_mov_b64_e32 v[88:89], v[20:21]
	v_mov_b64_e32 v[84:85], v[20:21]
	v_mov_b64_e32 v[80:81], v[20:21]
	v_mov_b64_e32 v[72:73], v[20:21]
	v_mov_b64_e32 v[76:77], v[20:21]
	v_bfe_u32 v2, v158, 4, 2
	s_mov_b32 s46, 0
	v_mov_b32_e32 v164, 0xf149f2ca
	v_mov_b32_e32 v165, 0
	v_mov_b32_e32 v163, 0
	v_mov_b32_e32 v162, 0xf149f2ca
	v_mov_b64_e32 v[62:63], v[18:19]
	v_mov_b64_e32 v[54:55], v[18:19]
	v_mov_b64_e32 v[58:59], v[18:19]
	v_mov_b64_e32 v[66:67], v[18:19]
	v_mov_b64_e32 v[134:135], v[18:19]
	v_mov_b64_e32 v[118:119], v[18:19]
	v_mov_b64_e32 v[106:107], v[18:19]
	v_mov_b64_e32 v[102:103], v[18:19]
	v_mov_b64_e32 v[98:99], v[18:19]
	v_mov_b64_e32 v[94:95], v[18:19]
	v_mov_b64_e32 v[90:91], v[18:19]
	v_mov_b64_e32 v[86:87], v[18:19]
	v_mov_b64_e32 v[82:83], v[18:19]
	v_mov_b64_e32 v[78:79], v[18:19]
	v_mov_b64_e32 v[70:71], v[18:19]
	v_and_b32_e32 v161, 15, v158
	v_lshlrev_b32_e32 v160, 3, v2
	v_mov_b64_e32 v[74:75], v[18:19]
	s_waitcnt vmcnt(0) lgkmcnt(0)
	v_ashrrev_i32_e32 v179, 12, v138
	v_and_b32_e32 v178, 3, v138
	v_bfe_u32 v177, v138, 2, 5
	v_bfe_u32 v176, v138, 7, 5
	v_cmp_lt_i32_e32 vcc, 0, v179
	s_and_saveexec_b64 s[30:31], vcc
	s_cbranch_execz .LBB0_2245
	v_mul_u32_u24_e32 v3, 0xc0, v178
	v_lshl_add_u32 v4, v177, 8, s42
	v_lshlrev_b32_e32 v18, 1, v3
	v_or_b32_e32 v30, v4, v161
	v_lshl_add_u64 v[4:5], s[12:13], 0, v[18:19]
	v_lshlrev_b32_e32 v2, 4, v2
	v_mov_b32_e32 v3, v19
	v_lshl_add_u64 v[20:21], v[4:5], 0, v[2:3]
	s_movk_i32 s38, 0x600
	v_mad_i64_i32 v[26:27], s[36:37], v30, s38, v[20:21]
	v_or_b32_e32 v30, 16, v30
	v_mad_i64_i32 v[20:21], s[36:37], v30, s38, v[20:21]
	s_mov_b32 s36, 0x2aaaaaab
	global_load_dwordx4 v[2:5], v[26:27], off
	global_load_dwordx4 v[6:9], v[26:27], off offset:64
	global_load_dwordx4 v[10:13], v[26:27], off offset:128
	global_load_dwordx4 v[14:17], v[26:27], off offset:192
	global_load_dwordx4 v[22:25], v[26:27], off offset:256
	s_nop 0
	global_load_dwordx4 v[26:29], v[26:27], off offset:320
	s_nop 0
	global_load_dwordx4 v[30:33], v[20:21], off
	global_load_dwordx4 v[34:37], v[20:21], off offset:64
	global_load_dwordx4 v[38:41], v[20:21], off offset:128
	global_load_dwordx4 v[42:45], v[20:21], off offset:192
	global_load_dwordx4 v[46:49], v[20:21], off offset:256
	global_load_dwordx4 v[50:53], v[20:21], off offset:320
	v_mul_hi_i32 v20, v158, s36
	v_lshrrev_b32_e32 v21, 31, v20
	v_ashrrev_i32_e32 v20, 2, v20
	v_add_u32_e32 v80, v20, v21
	v_add_u32_e32 v20, 0x200, v158
	v_mul_hi_i32 v21, v20, s36
	v_lshrrev_b32_e32 v54, 31, v21
	v_ashrrev_i32_e32 v21, 2, v21
	v_add_u32_e32 v81, v21, v54
	v_add_u32_e32 v54, 0x400, v158
	v_mul_hi_i32 v21, v54, s36
	v_lshrrev_b32_e32 v55, 31, v21
	v_ashrrev_i32_e32 v21, 2, v21
	v_add_u32_e32 v82, v21, v55
	s_movk_i32 s39, 0xffe8
	v_mad_u64_u32 v[54:55], s[36:37], v82, s39, v[54:55]
	v_lshlrev_b32_e32 v74, 21, v178
	v_mov_b32_e32 v75, v19
	v_ashrrev_i32_e32 v56, 3, v158
	v_ashrrev_i32_e32 v60, 3, v20
	v_lshl_add_u64 v[74:75], s[18:19], 0, v[74:75]
	v_lshlrev_b32_e32 v76, 11, v176
	v_mov_b32_e32 v77, v19
	v_lshlrev_b32_e32 v55, 4, v158
	v_ashrrev_i32_e32 v57, 31, v56
	v_ashrrev_i32_e32 v61, 31, v60
	v_mad_u64_u32 v[20:21], s[36:37], v81, s39, v[20:21]
	v_lshl_add_u64 v[74:75], v[74:75], 0, v[76:77]
	v_and_b32_e32 v76, 0x70, v55
	v_lshlrev_b64 v[58:59], 14, v[56:57]
	v_lshlrev_b64 v[62:63], 14, v[60:61]
	v_lshlrev_b32_e32 v64, 3, v54
	v_lshlrev_b32_e32 v21, 10, v176
	v_lshl_add_u64 v[74:75], v[74:75], 0, v[76:77]
	v_ashrrev_i32_e32 v65, 31, v64
	v_lshlrev_b32_e32 v66, 3, v20
	v_mad_u64_u32 v[68:69], s[36:37], v80, s39, v[158:159]
	v_lshl_add_u64 v[72:73], s[16:17], 0, v[18:19]
	v_lshl_add_u64 v[78:79], v[74:75], 0, v[62:63]
	v_lshl_add_u64 v[74:75], v[74:75], 0, v[58:59]
	v_add_u32_e32 v61, v82, v21
	v_ashrrev_i32_e32 v67, 31, v66
	v_mad_i64_i32 v[74:75], s[36:37], v61, s38, v[72:73]
	v_lshlrev_b64 v[64:65], 1, v[64:65]
	v_add_u32_e32 v69, v81, v21
	v_lshlrev_b32_e32 v70, 3, v68
	v_lshl_add_u64 v[74:75], v[74:75], 0, v[64:65]
	v_mad_i64_i32 v[78:79], s[36:37], v69, s38, v[72:73]
	v_lshlrev_b64 v[66:67], 1, v[66:67]
	v_ashrrev_i32_e32 v71, 31, v70
	v_lshl_add_u64 v[78:79], v[78:79], 0, v[66:67]
	global_load_dwordx4 v[126:129], v[74:75], off
	global_load_dwordx4 v[122:125], v[78:79], off
	v_add_u32_e32 v74, v21, v80
	v_mad_i64_i32 v[72:73], s[36:37], v74, s38, v[72:73]
	v_lshlrev_b64 v[70:71], 1, v[70:71]
	v_lshl_add_u64 v[72:73], v[72:73], 0, v[70:71]
	global_load_dwordx4 v[130:133], v[72:73], off
	v_and_b32_e32 v21, 48, v158
	v_add_u32_e32 v73, s11, v21
	v_mov_b32_e32 v21, s11
	s_movk_i32 s36, 0x190
	v_mad_u32_u24 v77, v161, s90, v21
	v_mul_lo_u32 v21, v80, s36
	v_add_u32_e32 v79, s11, v21
	v_mul_lo_u32 v21, v81, s36
	v_lshlrev_b32_e32 v81, 4, v20
	v_mul_lo_u32 v20, v82, s36
	v_add_u32_e32 v82, s11, v20
	v_or_b32_e32 v20, 16, v161
	v_mul_u32_u24_e32 v86, 0x90, v20
	v_mov_b32_e32 v20, 0x3d000000
; #define LAS __attribute__((address_space(3)))
; DI void u_attn2(Frame& F, int h, int qb, int sp, int ntile) {
;     ...
;     const int kt0 = 16 * sp;
;     ...
;     AT_LOAD(kt0)
;     for (int t = 0; t < ntile; ++t) {
;         const int kt = kt0 + t;
;         __syncthreads();
; #pragma unroll
;         for (int i = 0; i < 3; ++i) { const int p = tid + 512 * i, r = p / 24, cc = p - r * 24; *(LAS u32x4*)(Ks + r * 200 + cc * 8) = kreg[i]; }
; #pragma unroll
;         for (int i = 0; i < 2; ++i) { const int p = tid + 512 * i, r = p >> 3, cc = p & 7; *(LAS u32x4*)(Vs + r * 72 + cc * 8) = vreg[i]; }
;         __syncthreads();
;         if (t + 1 < ntile) AT_LOAD(kt + 1)
	v_add_u32_e32 v80, s11, v21
	v_mul_lo_u32 v84, v56, s90
	v_lshl_or_b32 v20, v178, 21, v20
	v_mov_b32_e32 v21, v19
	v_lshlrev_b32_e32 v56, 4, v138
	v_lshlrev_b32_e32 v83, 4, v54
	v_lshl_add_u64 v[54:55], v[20:21], 0, v[62:63]
	v_and_b32_e32 v56, 0xf800, v56
	v_mov_b32_e32 v57, v19
	v_lshl_add_u64 v[20:21], v[20:21], 0, v[58:59]
	v_lshl_add_u64 v[168:169], v[20:21], 0, v[56:57]
	v_mad_i64_i32 v[20:21], s[36:37], v61, s38, v[64:65]
	v_lshl_add_u64 v[20:21], v[20:21], 0, v[18:19]
	s_mov_b64 s[48:49], 0x3c418000
	v_lshl_add_u64 v[170:171], v[20:21], 0, s[48:49]
	v_mad_i64_i32 v[20:21], s[36:37], v69, s38, v[66:67]
	v_lshl_add_u64 v[20:21], v[20:21], 0, v[18:19]
	v_lshl_add_u64 v[172:173], v[20:21], 0, s[48:49]
	v_mad_i64_i32 v[20:21], s[36:37], v74, s38, v[70:71]
	v_lshl_add_u64 v[20:21], v[20:21], 0, v[18:19]
	v_add_u32_e32 v72, s11, v76
	v_mul_u32_u24_e32 v75, 0x90, v161
	v_add_u32_e32 v78, s11, v160
	v_lshlrev_b32_e32 v68, 4, v68
	v_mul_lo_u32 v60, v60, s90
	v_mul_u32_u24_e32 v85, 0x190, v161
	v_lshl_add_u64 v[166:167], v[54:55], 0, v[56:57]
	v_lshl_add_u64 v[174:175], v[20:21], 0, s[48:49]
	v_mov_b32_e32 v20, v19
	v_mov_b32_e32 v21, v19
	v_or_b32_e32 v166, v166, v76
	v_or_b32_e32 v168, v168, v76
	v_mov_b32_e32 v18, v19
	v_add_u32_e32 v182, v79, v68
	v_add_u32_e32 v183, v80, v81
	v_add_u32_e32 v184, v82, v83
	v_add_u32_e32 v185, v72, v84
	v_add_u32_e32 v186, v72, v60
	v_add_u32_e32 v187, v73, v85
	v_add_u32_e32 v188, v77, v160
	v_add_u32_e32 v189, v78, v86
	v_add_u32_e32 v190, v78, v75
	v_mov_b64_e32 v[76:77], v[20:21]
	v_mov_b64_e32 v[72:73], v[20:21]
	v_mov_b64_e32 v[80:81], v[20:21]
	v_mov_b64_e32 v[84:85], v[20:21]
	v_mov_b64_e32 v[88:89], v[20:21]
	v_mov_b64_e32 v[92:93], v[20:21]
	v_mov_b64_e32 v[96:97], v[20:21]
	v_mov_b64_e32 v[100:101], v[20:21]
	v_mov_b64_e32 v[104:105], v[20:21]
	v_mov_b64_e32 v[108:109], v[20:21]
	v_mov_b64_e32 v[120:121], v[20:21]
	v_mov_b64_e32 v[136:137], v[20:21]
	v_mov_b64_e32 v[68:69], v[20:21]
	v_mov_b64_e32 v[60:61], v[20:21]
	v_mov_b64_e32 v[56:57], v[20:21]
	v_mov_b64_e32 v[64:65], v[20:21]
	v_lshl_add_u32 v180, v177, 2, s43
	v_lshlrev_b32_e32 v181, 4, v176
	v_mov_b32_e32 v163, 0
	v_mov_b32_e32 v162, 0xf149f2ca
	s_mov_b64 s[36:37], 0
	v_mov_b64_e32 v[74:75], v[18:19]
	v_mov_b64_e32 v[70:71], v[18:19]
	v_mov_b64_e32 v[78:79], v[18:19]
	v_mov_b64_e32 v[82:83], v[18:19]
	v_mov_b64_e32 v[86:87], v[18:19]
	v_mov_b64_e32 v[90:91], v[18:19]
	v_mov_b64_e32 v[94:95], v[18:19]
	v_mov_b64_e32 v[98:99], v[18:19]
	v_mov_b64_e32 v[102:103], v[18:19]
	v_mov_b64_e32 v[106:107], v[18:19]
	v_mov_b64_e32 v[118:119], v[18:19]
	v_mov_b64_e32 v[134:135], v[18:19]
	v_mov_b32_e32 v164, 0xf149f2ca
	v_mov_b32_e32 v165, 0
	v_mov_b64_e32 v[66:67], v[18:19]
	v_mov_b64_e32 v[58:59], v[18:19]
	v_mov_b64_e32 v[54:55], v[18:19]
	v_mov_b64_e32 v[62:63], v[18:19]
	s_branch .LBB0_2237
.LBB0_2236:
	v_cmp_eq_u32_e32 vcc, s46, v179
	v_lshl_add_u64 v[166:167], v[166:167], 0, s[60:61]
	v_lshl_add_u64 v[168:169], v[168:169], 0, s[60:61]
	v_lshl_add_u64 v[170:171], v[170:171], 0, s[14:15]
	v_lshl_add_u64 v[172:173], v[172:173], 0, s[14:15]
	v_lshl_add_u64 v[174:175], v[174:175], 0, s[14:15]
	s_or_b64 s[36:37], vcc, s[36:37]
	s_mov_b32 s46, s45
	s_andn2_b64 exec, exec, s[36:37]
	s_cbranch_execz .LBB0_2244
.LBB0_2237:
	s_add_i32 s45, s46, 1
	s_barrier
	s_waitcnt vmcnt(0)
	ds_write_b128 v182, v[130:133]
	ds_write_b128 v183, v[122:125]
	ds_write_b128 v184, v[126:129]
	ds_write_b128 v185, v[110:113] offset:25600
	ds_write_b128 v186, v[114:117] offset:25600
	v_mov_b32_e32 v234, 0x42800000
	s_waitcnt lgkmcnt(0)
	s_barrier
	v_cmp_lt_i32_e32 vcc, s46, v179
	s_cbranch_vccz .Latt_noload
	v_lshl_add_u64 v[110:111], s[2:3], 0, v[168:169]
	v_lshl_add_u64 v[20:21], s[2:3], 0, v[166:167]
	s_nop 0
	global_load_dwordx4 v[110:113], v[110:111], off
	global_load_dwordx4 v[114:117], v[20:21], off
	v_cmp_lt_i32_e32 vcc, s45, v179
	s_cbranch_vccz .Latt_noload
	v_lshl_add_u64 v[20:21], s[2:3], 0, v[174:175]
	v_lshl_add_u64 v[122:123], s[2:3], 0, v[172:173]
	global_load_dwordx4 v[130:133], v[20:21], off
	s_nop 0
	global_load_dwordx4 v[122:125], v[122:123], off
	v_lshl_add_u64 v[20:21], s[2:3], 0, v[170:171]
	s_nop 0
	global_load_dwordx4 v[126:129], v[20:21], off
.Latt_noload:
	s_cmp_lt_i32 s24, 4
	s_cbranch_scc0 .Latt_gB
	s_cmp_eq_u32 s46, 0
	s_cbranch_scc1 .Latt_A_qk
	v_add3_u32 v18, s46, v181, -1
	v_cmp_le_i32_e32 vcc, v18, v180
	s_cbranch_vccz .Latt_A_qk
; #define MFMA16(a, b, c) __builtin_amdgcn_mfma_f32_16x16x32_bf16((a), (b), (c), 0, 0, 0)
; #define AT_VLD(dst, db_) { _Pragma("unroll") for (int s2 = 0; s2 < 2; ++s2) { const LAS bf16* vp = Vs + ((db_) * 16 + lc) * 72 + 32 * s2 + 4 * g4; \
;                     const u32x2 v0 = *(const LAS u32x2*)vp, v1 = *(const LAS u32x2*)(vp + 16); const u32x4 vw = (u32x4){v0.x, v0.y, v1.x, v1.y}; dst[s2] = __builtin_bit_cast(bf16x8, vw); } }
; DI void u_attn2(Frame& F, int h, int qb, int sp, int ntile) {
;     ...
;         if (kt <= cw) {
;             f32x4 s[4][2];
; #pragma unroll
;             for (int kb = 0; kb < 4; ++kb)
; #pragma unroll
;                 for (int qq = 0; qq < 2; ++qq) s[kb][qq] = (f32x4){0.f, 0.f, 0.f, 0.f};
;             {
;                 bf16x8 kfr[2][4];
; #pragma unroll
;                 for (int kb = 0; kb < 4; ++kb) kfr[0][kb] = ldfrag(Ks, 200, kb * 16, 0, lane);
; #pragma unroll
;                 for (int ks = 0; ks < 6; ++ks) {
;                     if (ks < 5) {
;     ...
;             {
;                 bf16x8 vfr[2][2];
;     ...
;                 AT_VLD(vfr[0], 0)
; #pragma unroll
;                 for (int db = 0; db < 8; ++db) {
;                     if (db < 7) AT_VLD(vfr[(db + 1) & 1], db + 1)
; #pragma unroll
;                     for (int s2 = 0; s2 < 2; ++s2)
; #pragma unroll
;                         for (int qq = 0; qq < 2; ++qq) o[db][qq] = MFMA16(vfr[db & 1][s2], pf[qq][s2], o[db][qq]);
;                 }
;     ...
;             }
	v_add_u32_e32 v140, 0x6000, v189
	ds_read2_b64 v[146:149], v140 offset0:128 offset1:132
	ds_read2_b64 v[244:247], v140 offset0:136 offset1:140
	v_add_u32_e32 v219, 0x6000, v188
	v_add_u32_e32 v140, 0x6800, v189
	ds_read2_b64 v[220:223], v219 offset0:128 offset1:132
	ds_read2_b64 v[224:227], v219 offset0:136 offset1:140
	s_waitcnt lgkmcnt(3)
	v_mfma_f32_16x16x32_bf16 v[106:109], v[146:149], v[198:201], v[106:109]
	v_mfma_f32_16x16x32_bf16 v[102:105], v[146:149], v[210:213], v[102:105]
	ds_read2_b64 v[146:149], v140 offset0:160 offset1:164
	s_waitcnt lgkmcnt(3)
	v_mfma_f32_16x16x32_bf16 v[106:109], v[244:247], v[192:195], v[106:109]
	v_mfma_f32_16x16x32_bf16 v[102:105], v[244:247], v[142:145], v[102:105]
	ds_read2_b64 v[244:247], v140 offset0:168 offset1:172
	v_add_u32_e32 v140, 0x7000, v189
	s_waitcnt lgkmcnt(1)
	v_mfma_f32_16x16x32_bf16 v[98:101], v[146:149], v[198:201], v[98:101]
	v_mfma_f32_16x16x32_bf16 v[94:97], v[146:149], v[210:213], v[94:97]
	ds_read2_b64 v[146:149], v140 offset0:192 offset1:196
	s_waitcnt lgkmcnt(1)
	v_mfma_f32_16x16x32_bf16 v[98:101], v[244:247], v[192:195], v[98:101]
	v_mfma_f32_16x16x32_bf16 v[94:97], v[244:247], v[142:145], v[94:97]
	ds_read2_b64 v[244:247], v140 offset0:200 offset1:204
	v_add_u32_e32 v140, 0x8800, v190
	s_waitcnt lgkmcnt(1)
	v_mfma_f32_16x16x32_bf16 v[90:93], v[146:149], v[198:201], v[90:93]
	v_mfma_f32_16x16x32_bf16 v[86:89], v[146:149], v[210:213], v[86:89]
	ds_read2_b64 v[146:149], v140 offset1:4
	s_waitcnt lgkmcnt(1)
	v_mfma_f32_16x16x32_bf16 v[90:93], v[244:247], v[192:195], v[90:93]
	v_mfma_f32_16x16x32_bf16 v[86:89], v[244:247], v[142:145], v[86:89]
	ds_read2_b64 v[244:247], v140 offset0:8 offset1:12
	v_add_u32_e32 v140, 0x9000, v190
	s_waitcnt lgkmcnt(1)
	v_mfma_f32_16x16x32_bf16 v[82:85], v[146:149], v[198:201], v[82:85]
	v_mfma_f32_16x16x32_bf16 v[78:81], v[146:149], v[210:213], v[78:81]
	ds_read2_b64 v[146:149], v140 offset0:32 offset1:36
	s_waitcnt lgkmcnt(1)
	v_mfma_f32_16x16x32_bf16 v[82:85], v[244:247], v[192:195], v[82:85]
	v_mfma_f32_16x16x32_bf16 v[78:81], v[244:247], v[142:145], v[78:81]
	ds_read2_b64 v[244:247], v140 offset0:40 offset1:44
	v_add_u32_e32 v140, 0x9800, v190
	s_waitcnt lgkmcnt(1)
	v_mfma_f32_16x16x32_bf16 v[70:73], v[146:149], v[198:201], v[70:73]
	v_mfma_f32_16x16x32_bf16 v[74:77], v[146:149], v[210:213], v[74:77]
	ds_read2_b64 v[146:149], v140 offset0:64 offset1:68
	s_waitcnt lgkmcnt(1)
	v_mfma_f32_16x16x32_bf16 v[70:73], v[244:247], v[192:195], v[70:73]
	v_mfma_f32_16x16x32_bf16 v[74:77], v[244:247], v[142:145], v[74:77]
	ds_read2_b64 v[244:247], v140 offset0:72 offset1:76
	v_add_u32_e32 v140, 0xa000, v190
	s_waitcnt lgkmcnt(1)
	v_mfma_f32_16x16x32_bf16 v[66:69], v[146:149], v[198:201], v[66:69]
	v_mfma_f32_16x16x32_bf16 v[58:61], v[146:149], v[210:213], v[58:61]
	ds_read2_b64 v[146:149], v140 offset0:96 offset1:100
	ds_read2_b64 v[150:153], v140 offset0:104 offset1:108
	s_waitcnt lgkmcnt(2)
	v_mfma_f32_16x16x32_bf16 v[66:69], v[244:247], v[192:195], v[66:69]
	v_mfma_f32_16x16x32_bf16 v[58:61], v[244:247], v[142:145], v[58:61]
	v_mfma_f32_16x16x32_bf16 v[134:137], v[220:223], v[198:201], v[134:137]
	v_mfma_f32_16x16x32_bf16 v[118:121], v[220:223], v[210:213], v[118:121]
	s_waitcnt lgkmcnt(1)
	v_mfma_f32_16x16x32_bf16 v[54:57], v[146:149], v[198:201], v[54:57]
	v_mfma_f32_16x16x32_bf16 v[62:65], v[146:149], v[210:213], v[62:65]
	v_mfma_f32_16x16x32_bf16 v[134:137], v[224:227], v[192:195], v[134:137]
	v_mfma_f32_16x16x32_bf16 v[118:121], v[224:227], v[142:145], v[118:121]
	s_waitcnt lgkmcnt(0)
	v_mfma_f32_16x16x32_bf16 v[54:57], v[150:153], v[192:195], v[54:57]
	v_mfma_f32_16x16x32_bf16 v[62:65], v[150:153], v[142:145], v[62:65]
.Latt_A_qk:
	v_cmp_lt_i32_e32 vcc, s46, v179
	s_cbranch_vccz .LBB0_2236
	v_add_u32_e32 v18, s46, v181
	v_cmp_le_i32_e32 vcc, v18, v180
	s_cbranch_vccz .LBB0_2236
	ds_read_b128 v[138:141], v187
	ds_read_b128 v[142:145], v187 offset:6400
	ds_read_b128 v[146:149], v187 offset:12800
	ds_read_b128 v[150:153], v187 offset:19200
	ds_read_b128 v[154:157], v187 offset:64
	ds_read_b128 v[192:195], v187 offset:6464
	ds_read_b128 v[210:213], v187 offset:12864
	ds_read_b128 v[214:217], v187 offset:19264
	s_waitcnt lgkmcnt(7)
	v_mfma_f32_16x16x32_bf16 v[218:221], v[138:141], v[2:5], 0
	ds_read_b128 v[244:247], v187 offset:128
	ds_read_b128 v[248:251], v187 offset:6528
	ds_read_b128 v[198:201], v187 offset:12928
	ds_read_b128 v[230:233], v187 offset:19328
	v_mov_b32_e32 v234, 0x42800000
	v_mfma_f32_16x16x32_bf16 v[138:141], v[138:141], v[30:33], 0
	s_waitcnt lgkmcnt(10)
	v_mfma_f32_16x16x32_bf16 v[222:225], v[142:145], v[2:5], 0
	v_mfma_f32_16x16x32_bf16 v[142:145], v[142:145], v[30:33], 0
	s_waitcnt lgkmcnt(9)
	v_mfma_f32_16x16x32_bf16 v[226:229], v[146:149], v[2:5], 0
	s_waitcnt lgkmcnt(7)
	v_mfma_f32_16x16x32_bf16 v[218:221], v[154:157], v[6:9], v[218:221]
	v_mfma_f32_16x16x32_bf16 v[146:149], v[146:149], v[30:33], 0
	v_mfma_f32_16x16x32_bf16 v[240:243], v[150:153], v[2:5], 0
	v_mfma_f32_16x16x32_bf16 v[150:153], v[150:153], v[30:33], 0
	v_mfma_f32_16x16x32_bf16 v[138:141], v[154:157], v[34:37], v[138:141]
	s_waitcnt lgkmcnt(6)
	v_mfma_f32_16x16x32_bf16 v[154:157], v[192:195], v[6:9], v[222:225]
	v_mfma_f32_16x16x32_bf16 v[142:145], v[192:195], v[34:37], v[142:145]
	s_waitcnt lgkmcnt(5)
	v_mfma_f32_16x16x32_bf16 v[192:195], v[210:213], v[6:9], v[226:229]
	s_waitcnt lgkmcnt(3)
; DI float xr16_max(float x) { float a = x, b = x; XR_SWAP("v_permlane16_swap_b32", a, b); return fmaxf(a, b); }
; DI float xr32_max(float x) { float a = x, b = x; XR_SWAP("v_permlane32_swap_b32", a, b); return fmaxf(a, b); }
; DI float xr16_sum(float x) { float a = x, b = x; XR_SWAP("v_permlane16_swap_b32", a, b); return a + b; }
; DI float xr32_sum(float x) { float a = x, b = x; XR_SWAP("v_permlane32_swap_b32", a, b); return a + b; }
; #define MFMA16(a, b, c) __builtin_amdgcn_mfma_f32_16x16x32_bf16((a), (b), (c), 0, 0, 0)
; DI void u_attn2(Frame& F, int h, int qb, int sp, int ntile) {
;     ...
;             {
;                 bf16x8 kfr[2][4];
; #pragma unroll
;                 for (int kb = 0; kb < 4; ++kb) kfr[0][kb] = ldfrag(Ks, 200, kb * 16, 0, lane);
; #pragma unroll
;                 for (int ks = 0; ks < 6; ++ks) {
;                     if (ks < 5) {
; #pragma unroll
;                         for (int kb = 0; kb < 4; ++kb) kfr[(ks + 1) & 1][kb] = ldfrag(Ks, 200, kb * 16, (ks + 1) * 32, lane); }
; #pragma unroll
;                     for (int kb = 0; kb < 4; ++kb)
; #pragma unroll
;                         for (int qq = 0; qq < 2; ++qq) s[kb][qq] = MFMA16(kfr[ks & 1][kb], qf[qq][ks], s[kb][qq]);
;                 }
;             }
;             bf16x8 pf[2][2];
; #pragma unroll
;             for (int qq = 0; qq < 2; ++qq) {
;                 float mx = -1e30f;
; #pragma unroll
;                 for (int kb = 0; kb < 4; ++kb) mx = fmaxf(mx, fmaxf(fmaxf(s[kb][qq][0], s[kb][qq][1]), fmaxf(s[kb][qq][2], s[kb][qq][3])));
;                 mx = xr32_max(xr16_max(mx));
;                 const float mn = fmaxf(mrun[qq], mx), alpha = __builtin_amdgcn_exp2f(mrun[qq] - mn); mrun[qq] = mn;
;                 float ps = 0.f; float p[16];
; #pragma unroll
;                 for (int kb = 0; kb < 4; ++kb)
; #pragma unroll
;                     for (int r = 0; r < 4; ++r) { p[kb * 4 + r] = __builtin_amdgcn_exp2f(s[kb][qq][r] - mn); ps += p[kb * 4 + r]; }
;                 ps = xr32_sum(xr16_sum(ps));
;                 lrun[qq] = lrun[qq] * alpha + ps;
; if (__builtin_amdgcn_ballot_w64(alpha != 1.0f) != 0ull) {
; #pragma unroll
;                     for (int db = 0; db < 8; ++db) o[db][qq] = o[db][qq] * alpha; }
	v_mfma_f32_16x16x32_bf16 v[218:221], v[244:247], v[10:13], v[218:221]
	v_mfma_f32_16x16x32_bf16 v[146:149], v[210:213], v[34:37], v[146:149]
	v_mfma_f32_16x16x32_bf16 v[210:213], v[214:217], v[6:9], v[240:243]
	v_mfma_f32_16x16x32_bf16 v[150:153], v[214:217], v[34:37], v[150:153]
	ds_read_b128 v[214:217], v187 offset:192
	ds_read_b128 v[222:225], v187 offset:6592
	ds_read_b128 v[226:229], v187 offset:12992
	ds_read_b128 v[240:243], v187 offset:19392
	v_mfma_f32_16x16x32_bf16 v[138:141], v[244:247], v[38:41], v[138:141]
	s_waitcnt lgkmcnt(6)
	v_mfma_f32_16x16x32_bf16 v[154:157], v[248:251], v[10:13], v[154:157]
	v_mfma_f32_16x16x32_bf16 v[142:145], v[248:251], v[38:41], v[142:145]
	s_waitcnt lgkmcnt(5)
	v_mfma_f32_16x16x32_bf16 v[192:195], v[198:201], v[10:13], v[192:195]
	s_waitcnt lgkmcnt(3)
	v_mfma_f32_16x16x32_bf16 v[218:221], v[214:217], v[14:17], v[218:221]
	v_mfma_f32_16x16x32_bf16 v[146:149], v[198:201], v[38:41], v[146:149]
	v_mfma_f32_16x16x32_bf16 v[198:201], v[230:233], v[10:13], v[210:213]
	v_mfma_f32_16x16x32_bf16 v[150:153], v[230:233], v[38:41], v[150:153]
	s_nop 1
	ds_read_b128 v[210:213], v187 offset:256
	ds_read_b128 v[230:233], v187 offset:6656
	ds_read_b128 v[244:247], v187 offset:13056
	ds_read_b128 v[248:251], v187 offset:19456
	v_mfma_f32_16x16x32_bf16 v[138:141], v[214:217], v[42:45], v[138:141]
	s_waitcnt lgkmcnt(6)
	v_mfma_f32_16x16x32_bf16 v[154:157], v[222:225], v[14:17], v[154:157]
	v_mfma_f32_16x16x32_bf16 v[142:145], v[222:225], v[42:45], v[142:145]
	s_waitcnt lgkmcnt(5)
	v_mfma_f32_16x16x32_bf16 v[192:195], v[226:229], v[14:17], v[192:195]
	s_waitcnt lgkmcnt(3)
	v_mfma_f32_16x16x32_bf16 v[218:221], v[210:213], v[22:25], v[218:221]
	v_mfma_f32_16x16x32_bf16 v[198:201], v[240:243], v[14:17], v[198:201]
	v_mfma_f32_16x16x32_bf16 v[150:153], v[240:243], v[42:45], v[150:153]
	v_mfma_f32_16x16x32_bf16 v[138:141], v[210:213], v[46:49], v[138:141]
	s_waitcnt lgkmcnt(2)
	v_mfma_f32_16x16x32_bf16 v[154:157], v[230:233], v[22:25], v[154:157]
	v_mfma_f32_16x16x32_bf16 v[146:149], v[226:229], v[42:45], v[146:149]
	ds_read_b128 v[214:217], v187 offset:320
	ds_read_b128 v[222:225], v187 offset:6720
	ds_read_b128 v[226:229], v187 offset:13120
	ds_read_b128 v[240:243], v187 offset:19520
	v_mfma_f32_16x16x32_bf16 v[142:145], v[230:233], v[46:49], v[142:145]
	s_waitcnt lgkmcnt(5)
	v_mfma_f32_16x16x32_bf16 v[192:195], v[244:247], v[22:25], v[192:195]
	s_waitcnt lgkmcnt(3)
	v_mfma_f32_16x16x32_bf16 v[218:221], v[214:217], v[26:29], v[218:221]
	v_mfma_f32_16x16x32_bf16 v[198:201], v[248:251], v[22:25], v[198:201]
	v_mfma_f32_16x16x32_bf16 v[230:233], v[248:251], v[46:49], v[150:153]
	v_mfma_f32_16x16x32_bf16 v[150:153], v[214:217], v[50:53], v[138:141]
	s_waitcnt lgkmcnt(2)
	v_mfma_f32_16x16x32_bf16 v[214:217], v[222:225], v[26:29], v[154:157]
	v_mfma_f32_16x16x32_bf16 v[210:213], v[244:247], v[46:49], v[146:149]
	v_mfma_f32_16x16x32_bf16 v[146:149], v[222:225], v[50:53], v[142:145]
	s_waitcnt lgkmcnt(1)
	v_mfma_f32_16x16x32_bf16 v[222:225], v[226:229], v[26:29], v[192:195]
	s_waitcnt lgkmcnt(0)
	v_mfma_f32_16x16x32_bf16 v[154:157], v[240:243], v[26:29], v[198:201]
	v_mfma_f32_16x16x32_bf16 v[138:141], v[240:243], v[50:53], v[230:233]
	s_nop 1
	v_mfma_f32_16x16x32_bf16 v[142:145], v[226:229], v[50:53], v[210:213]
	s_nop 7
	s_nop 1
	v_max_f32_e32 v18, v220, v221
	v_max3_f32 v18, v218, v219, v18
	v_max_f32_e32 v20, v216, v217
	v_max3_f32 v20, v214, v215, v20
	v_max3_f32 v18, v18, s1, v20
	v_max_f32_e32 v20, v224, v225
	v_max_f32_e32 v21, v156, v157
	v_max3_f32 v20, v222, v223, v20
	v_max3_f32 v21, v154, v155, v21
	v_max3_f32 v18, v18, v20, v21
	v_mov_b32_e32 v20, v18
	s_nop 1
	v_permlane16_swap_b32 v18, v20
	s_nop 0
	v_max_f32_e32 v18, v18, v20
	v_mov_b32_e32 v20, v18
	s_nop 1
	v_permlane32_swap_b32 v18, v20
	s_nop 0
	v_max3_f32 v21, v164, v18, v20
	v_sub_f32_e32 v20, v218, v21
	v_sub_f32_e32 v18, v164, v21
	v_exp_f32_e32 v192, v20
	v_sub_f32_e32 v164, v219, v21
	v_exp_f32_e32 v194, v164
	v_sub_f32_e32 v164, v220, v21
	v_exp_f32_e32 v164, v164
	v_sub_f32_e32 v191, v221, v21
	v_exp_f32_e32 v191, v191
	v_sub_f32_e32 v193, v214, v21
	v_add_f32_e32 v20, 0, v192
	v_exp_f32_e32 v193, v193
	v_sub_f32_e32 v195, v215, v21
	v_add_f32_e32 v20, v194, v20
	v_exp_f32_e32 v195, v195
	v_sub_f32_e32 v198, v216, v21
	v_add_f32_e32 v20, v164, v20
	v_exp_f32_e32 v203, v198
	v_sub_f32_e32 v198, v217, v21
	v_add_f32_e32 v20, v191, v20
	v_exp_f32_e32 v210, v198
	v_sub_f32_e32 v198, v222, v21
	v_add_f32_e32 v20, v193, v20
	v_exp_f32_e32 v211, v198
	v_sub_f32_e32 v198, v223, v21
	v_add_f32_e32 v20, v195, v20
	v_exp_f32_e32 v212, v198
	v_sub_f32_e32 v198, v224, v21
	v_add_f32_e32 v20, v203, v20
	v_exp_f32_e32 v213, v198
	v_sub_f32_e32 v198, v225, v21
	v_add_f32_e32 v20, v210, v20
	v_exp_f32_e32 v214, v198
	v_sub_f32_e32 v154, v154, v21
	v_add_f32_e32 v20, v211, v20
	v_exp_f32_e32 v215, v154
	v_sub_f32_e32 v154, v155, v21
	v_add_f32_e32 v20, v212, v20
	v_exp_f32_e32 v217, v154
	v_sub_f32_e32 v154, v156, v21
	v_add_f32_e32 v20, v213, v20
	v_exp_f32_e32 v156, v154
	v_sub_f32_e32 v154, v157, v21
	v_add_f32_e32 v20, v214, v20
	v_exp_f32_e32 v157, v154
	v_add_f32_e32 v20, v215, v20
	v_add_f32_e32 v20, v217, v20
	v_add_f32_e32 v20, v156, v20
	v_add_f32_e32 v20, v157, v20
	v_exp_f32_e32 v18, v18
	v_mov_b32_e32 v154, v20
	s_nop 1
	v_permlane16_swap_b32 v20, v154
	v_cmp_neq_f32_e32 vcc, 1.0, v18
	v_add_f32_e32 v154, v20, v154
	v_mov_b32_e32 v155, v154
	s_nop 1
	v_permlane32_swap_b32 v154, v155
	s_cbranch_vccz .Latt_r0_A
	v_pk_mul_f32 v[136:137], v[136:137], v[18:19] op_sel_hi:[1,0]
	v_pk_mul_f32 v[134:135], v[134:135], v[18:19] op_sel_hi:[1,0]
	v_pk_mul_f32 v[108:109], v[108:109], v[18:19] op_sel_hi:[1,0]
	v_pk_mul_f32 v[106:107], v[106:107], v[18:19] op_sel_hi:[1,0]
	v_pk_mul_f32 v[100:101], v[100:101], v[18:19] op_sel_hi:[1,0]
	v_pk_mul_f32 v[98:99], v[98:99], v[18:19] op_sel_hi:[1,0]
	v_pk_mul_f32 v[92:93], v[92:93], v[18:19] op_sel_hi:[1,0]
	v_pk_mul_f32 v[90:91], v[90:91], v[18:19] op_sel_hi:[1,0]
	v_pk_mul_f32 v[84:85], v[84:85], v[18:19] op_sel_hi:[1,0]
	v_pk_mul_f32 v[82:83], v[82:83], v[18:19] op_sel_hi:[1,0]
	v_pk_mul_f32 v[72:73], v[72:73], v[18:19] op_sel_hi:[1,0]
	v_pk_mul_f32 v[70:71], v[70:71], v[18:19] op_sel_hi:[1,0]
	v_pk_mul_f32 v[68:69], v[68:69], v[18:19] op_sel_hi:[1,0]
	v_pk_mul_f32 v[66:67], v[66:67], v[18:19] op_sel_hi:[1,0]
	v_pk_mul_f32 v[56:57], v[56:57], v[18:19] op_sel_hi:[1,0]
	v_pk_mul_f32 v[54:55], v[54:55], v[18:19] op_sel_hi:[1,0]
; DI unsigned pk2(float lo, float hi) { const f32x2 v = {lo, hi}; const bf16x2_t b = __builtin_convertvector(v, bf16x2_t); return __builtin_bit_cast(unsigned, b); }
; DI float xr16_max(float x) { float a = x, b = x; XR_SWAP("v_permlane16_swap_b32", a, b); return fmaxf(a, b); }
; DI float xr32_max(float x) { float a = x, b = x; XR_SWAP("v_permlane32_swap_b32", a, b); return fmaxf(a, b); }
; DI float xr16_sum(float x) { float a = x, b = x; XR_SWAP("v_permlane16_swap_b32", a, b); return a + b; }
; DI float xr32_sum(float x) { float a = x, b = x; XR_SWAP("v_permlane32_swap_b32", a, b); return a + b; }
; DI void u_attn2(Frame& F, int h, int qb, int sp, int ntile) {
;     ...
;             for (int qq = 0; qq < 2; ++qq) {
;                 float mx = -1e30f;
; #pragma unroll
;                 for (int kb = 0; kb < 4; ++kb) mx = fmaxf(mx, fmaxf(fmaxf(s[kb][qq][0], s[kb][qq][1]), fmaxf(s[kb][qq][2], s[kb][qq][3])));
;                 mx = xr32_max(xr16_max(mx));
;                 const float mn = fmaxf(mrun[qq], mx), alpha = __builtin_amdgcn_exp2f(mrun[qq] - mn); mrun[qq] = mn;
;                 float ps = 0.f; float p[16];
; #pragma unroll
;                 for (int kb = 0; kb < 4; ++kb)
; #pragma unroll
;                     for (int r = 0; r < 4; ++r) { p[kb * 4 + r] = __builtin_amdgcn_exp2f(s[kb][qq][r] - mn); ps += p[kb * 4 + r]; }
;                 ps = xr32_sum(xr16_sum(ps));
;                 lrun[qq] = lrun[qq] * alpha + ps;
; if (__builtin_amdgcn_ballot_w64(alpha != 1.0f) != 0ull) {
; #pragma unroll
;                     for (int db = 0; db < 8; ++db) o[db][qq] = o[db][qq] * alpha; }
; #pragma unroll
;                 for (int s2 = 0; s2 < 2; ++s2) { u32x4 pw; pw.x = pk2(p[8 * s2], p[8 * s2 + 1]); pw.y = pk2(p[8 * s2 + 2], p[8 * s2 + 3]); pw.z = pk2(p[8 * s2 + 4], p[8 * s2 + 5]); pw.w = pk2(p[8 * s2 + 6], p[8 * s2 + 7]); pf[qq][s2] = __builtin_bit_cast(bf16x8, pw); }
.Latt_r0_A:
	v_max_f32_e32 v20, v152, v153
	v_max_f32_e32 v198, v148, v149
	v_max3_f32 v20, v150, v151, v20
	v_max3_f32 v198, v146, v147, v198
	v_max3_f32 v20, v20, s1, v198
	v_max_f32_e32 v198, v144, v145
	v_max_f32_e32 v199, v140, v141
	v_max3_f32 v198, v142, v143, v198
	v_max3_f32 v199, v138, v139, v199
	v_max3_f32 v20, v20, v198, v199
	v_mov_b32_e32 v198, v20
	s_nop 1
	v_permlane16_swap_b32 v20, v198
	s_nop 0
	v_max_f32_e32 v20, v20, v198
	v_mov_b32_e32 v198, v20
	s_nop 1
	v_permlane32_swap_b32 v20, v198
	s_nop 0
	v_max3_f32 v216, v162, v20, v198
	v_sub_f32_e32 v150, v150, v216
	v_sub_f32_e32 v20, v162, v216
	v_exp_f32_e32 v162, v150
	v_sub_f32_e32 v150, v151, v216
	v_exp_f32_e32 v218, v150
	v_sub_f32_e32 v150, v152, v216
	v_exp_f32_e32 v150, v150
	v_sub_f32_e32 v151, v153, v216
	v_exp_f32_e32 v151, v151
	v_sub_f32_e32 v146, v146, v216
	v_add_f32_e32 v152, 0, v162
	v_exp_f32_e32 v146, v146
	v_sub_f32_e32 v147, v147, v216
	v_add_f32_e32 v152, v218, v152
	v_exp_f32_e32 v147, v147
	v_sub_f32_e32 v148, v148, v216
	v_add_f32_e32 v152, v150, v152
	v_exp_f32_e32 v148, v148
	v_sub_f32_e32 v149, v149, v216
	v_add_f32_e32 v152, v151, v152
	v_exp_f32_e32 v149, v149
	v_sub_f32_e32 v142, v142, v216
	v_add_f32_e32 v152, v146, v152
	v_exp_f32_e32 v142, v142
	v_sub_f32_e32 v143, v143, v216
	v_add_f32_e32 v152, v147, v152
	v_exp_f32_e32 v143, v143
	v_sub_f32_e32 v144, v144, v216
	v_add_f32_e32 v152, v148, v152
	v_exp_f32_e32 v144, v144
	v_sub_f32_e32 v145, v145, v216
	v_add_f32_e32 v152, v149, v152
	v_exp_f32_e32 v145, v145
	v_add_f32_e32 v152, v142, v152
	v_add_f32_e32 v152, v143, v152
	v_add_f32_e32 v152, v144, v152
	v_sub_f32_e32 v138, v138, v216
	v_add_f32_e32 v198, v145, v152
	v_exp_f32_e32 v152, v138
	v_sub_f32_e32 v138, v139, v216
	v_exp_f32_e32 v153, v138
	v_sub_f32_e32 v138, v140, v216
	v_exp_f32_e32 v140, v138
	v_sub_f32_e32 v138, v141, v216
	v_exp_f32_e32 v141, v138
	v_add_f32_e32 v138, v152, v198
	v_add_f32_e32 v138, v153, v138
	v_add_f32_e32 v138, v140, v138
	v_add_f32_e32 v138, v141, v138
	v_exp_f32_e32 v20, v20
	v_mov_b32_e32 v139, v138
	s_nop 1
	v_permlane16_swap_b32 v138, v139
	v_cmp_neq_f32_e32 vcc, 1.0, v20
	v_add_f32_e32 v138, v138, v139
	v_mov_b32_e32 v139, v138
	s_nop 1
	v_permlane32_swap_b32 v138, v139
	s_cbranch_vccz .Latt_r1_A
	v_pk_mul_f32 v[120:121], v[120:121], v[20:21] op_sel_hi:[1,0]
	v_pk_mul_f32 v[118:119], v[118:119], v[20:21] op_sel_hi:[1,0]
	v_pk_mul_f32 v[104:105], v[104:105], v[20:21] op_sel_hi:[1,0]
	v_pk_mul_f32 v[102:103], v[102:103], v[20:21] op_sel_hi:[1,0]
	v_pk_mul_f32 v[96:97], v[96:97], v[20:21] op_sel_hi:[1,0]
	v_pk_mul_f32 v[94:95], v[94:95], v[20:21] op_sel_hi:[1,0]
	v_pk_mul_f32 v[88:89], v[88:89], v[20:21] op_sel_hi:[1,0]
	v_pk_mul_f32 v[86:87], v[86:87], v[20:21] op_sel_hi:[1,0]
	v_pk_mul_f32 v[80:81], v[80:81], v[20:21] op_sel_hi:[1,0]
	v_pk_mul_f32 v[78:79], v[78:79], v[20:21] op_sel_hi:[1,0]
	v_pk_mul_f32 v[76:77], v[76:77], v[20:21] op_sel_hi:[1,0]
	v_pk_mul_f32 v[74:75], v[74:75], v[20:21] op_sel_hi:[1,0]
	v_pk_mul_f32 v[60:61], v[60:61], v[20:21] op_sel_hi:[1,0]
	v_pk_mul_f32 v[58:59], v[58:59], v[20:21] op_sel_hi:[1,0]
	v_pk_mul_f32 v[64:65], v[64:65], v[20:21] op_sel_hi:[1,0]
	v_pk_mul_f32 v[62:63], v[62:63], v[20:21] op_sel_hi:[1,0]
.Latt_r1_A:
	v_cvt_pk_bf16_f32 v142, v142, v143
	v_cvt_pk_bf16_f32 v143, v144, v145
	v_cvt_pk_bf16_f32 v145, v140, v141
	v_cvt_pk_bf16_f32 v198, v192, v194
	v_cvt_pk_bf16_f32 v200, v193, v195
	v_cvt_pk_bf16_f32 v192, v211, v212
	v_cvt_pk_bf16_f32 v193, v213, v214
	v_cvt_pk_bf16_f32 v212, v146, v147
	v_cvt_pk_bf16_f32 v213, v148, v149
	v_cvt_pk_bf16_f32 v199, v164, v191
	v_cvt_pk_bf16_f32 v201, v203, v210
	v_cvt_pk_bf16_f32 v210, v162, v218
	v_cvt_pk_bf16_f32 v211, v150, v151
	v_cvt_pk_bf16_f32 v194, v215, v217
	v_cvt_pk_bf16_f32 v195, v156, v157
	v_cvt_pk_bf16_f32 v144, v152, v153
	v_add_f32_e32 v138, v138, v139
	v_fmac_f32_e32 v138, v163, v20
	v_add_f32_e32 v20, v154, v155
	v_fmac_f32_e32 v20, v165, v18
	v_mov_b32_e32 v165, v20
	v_mov_b32_e32 v163, v138
	v_mov_b32_e32 v164, v21
	v_mov_b32_e32 v162, v216
	s_branch .LBB0_2236
; DI float xr16_max(float x) { float a = x, b = x; XR_SWAP("v_permlane16_swap_b32", a, b); return fmaxf(a, b); }
; DI float xr32_max(float x) { float a = x, b = x; XR_SWAP("v_permlane32_swap_b32", a, b); return fmaxf(a, b); }
; DI float xr16_sum(float x) { float a = x, b = x; XR_SWAP("v_permlane16_swap_b32", a, b); return a + b; }
; DI float xr32_sum(float x) { float a = x, b = x; XR_SWAP("v_permlane32_swap_b32", a, b); return a + b; }
; DI void u_attn2(Frame& F, int h, int qb, int sp, int ntile) {
;     ...
;             for (int qq = 0; qq < 2; ++qq) {
;                 float mx = -1e30f;
; #pragma unroll
;                 for (int kb = 0; kb < 4; ++kb) mx = fmaxf(mx, fmaxf(fmaxf(s[kb][qq][0], s[kb][qq][1]), fmaxf(s[kb][qq][2], s[kb][qq][3])));
;                 mx = xr32_max(xr16_max(mx));
;                 const float mn = fmaxf(mrun[qq], mx), alpha = __builtin_amdgcn_exp2f(mrun[qq] - mn); mrun[qq] = mn;
;                 float ps = 0.f; float p[16];
; #pragma unroll
;                 for (int kb = 0; kb < 4; ++kb)
; #pragma unroll
;                     for (int r = 0; r < 4; ++r) { p[kb * 4 + r] = __builtin_amdgcn_exp2f(s[kb][qq][r] - mn); ps += p[kb * 4 + r]; }
;                 ps = xr32_sum(xr16_sum(ps));
;                 lrun[qq] = lrun[qq] * alpha + ps;
; if (__builtin_amdgcn_ballot_w64(alpha != 1.0f) != 0ull) {
; #pragma unroll
;                     for (int db = 0; db < 8; ++db) o[db][qq] = o[db][qq] * alpha; }
.Latt_gB:
	s_cmp_eq_u32 s46, 0
	s_cbranch_scc1 .Latt_B_qk
	v_add3_u32 v18, s46, v181, -1
	v_cmp_le_i32_e32 vcc, v18, v180
	s_cbranch_vccz .Latt_B_qk
	v_max_f32_e32 v18, v220, v221
	v_max3_f32 v18, v218, v219, v18
	v_max_f32_e32 v20, v216, v217
	v_max3_f32 v20, v214, v215, v20
	v_max3_f32 v18, v18, s1, v20
	v_max_f32_e32 v20, v224, v225
	v_max_f32_e32 v21, v156, v157
	v_max3_f32 v20, v222, v223, v20
	v_max3_f32 v21, v154, v155, v21
	v_max3_f32 v18, v18, v20, v21
	v_mov_b32_e32 v20, v18
	s_nop 1
	v_permlane16_swap_b32 v18, v20
	s_nop 0
	v_max_f32_e32 v18, v18, v20
	v_mov_b32_e32 v20, v18
	s_nop 1
	v_permlane32_swap_b32 v18, v20
	s_nop 0
	v_max3_f32 v21, v164, v18, v20
	v_sub_f32_e32 v20, v218, v21
	v_sub_f32_e32 v18, v164, v21
	v_exp_f32_e32 v192, v20
	v_sub_f32_e32 v164, v219, v21
	v_exp_f32_e32 v194, v164
	v_sub_f32_e32 v164, v220, v21
	v_exp_f32_e32 v164, v164
	v_sub_f32_e32 v191, v221, v21
	v_exp_f32_e32 v191, v191
	v_sub_f32_e32 v193, v214, v21
	v_add_f32_e32 v20, 0, v192
	v_exp_f32_e32 v193, v193
	v_sub_f32_e32 v195, v215, v21
	v_add_f32_e32 v20, v194, v20
	v_exp_f32_e32 v195, v195
	v_sub_f32_e32 v198, v216, v21
	v_add_f32_e32 v20, v164, v20
	v_exp_f32_e32 v203, v198
	v_sub_f32_e32 v198, v217, v21
	v_add_f32_e32 v20, v191, v20
	v_exp_f32_e32 v210, v198
	v_sub_f32_e32 v198, v222, v21
	v_add_f32_e32 v20, v193, v20
	v_exp_f32_e32 v211, v198
	v_sub_f32_e32 v198, v223, v21
	v_add_f32_e32 v20, v195, v20
	v_exp_f32_e32 v212, v198
	v_sub_f32_e32 v198, v224, v21
	v_add_f32_e32 v20, v203, v20
	v_exp_f32_e32 v213, v198
	v_sub_f32_e32 v198, v225, v21
	v_add_f32_e32 v20, v210, v20
	v_exp_f32_e32 v214, v198
	v_sub_f32_e32 v154, v154, v21
	v_add_f32_e32 v20, v211, v20
	v_exp_f32_e32 v215, v154
	v_sub_f32_e32 v154, v155, v21
	v_add_f32_e32 v20, v212, v20
	v_exp_f32_e32 v217, v154
	v_sub_f32_e32 v154, v156, v21
	v_add_f32_e32 v20, v213, v20
	v_exp_f32_e32 v156, v154
	v_sub_f32_e32 v154, v157, v21
	v_add_f32_e32 v20, v214, v20
	v_exp_f32_e32 v157, v154
	v_add_f32_e32 v20, v215, v20
	v_add_f32_e32 v20, v217, v20
	v_add_f32_e32 v20, v156, v20
	v_add_f32_e32 v20, v157, v20
	v_exp_f32_e32 v18, v18
	v_mov_b32_e32 v154, v20
	s_nop 1
	v_permlane16_swap_b32 v20, v154
	v_cmp_neq_f32_e32 vcc, 1.0, v18
	v_add_f32_e32 v154, v20, v154
	v_mov_b32_e32 v155, v154
	s_nop 1
	v_permlane32_swap_b32 v154, v155
	s_cbranch_vccz .Latt_r0_B
	v_pk_mul_f32 v[136:137], v[136:137], v[18:19] op_sel_hi:[1,0]
	v_pk_mul_f32 v[134:135], v[134:135], v[18:19] op_sel_hi:[1,0]
	v_pk_mul_f32 v[108:109], v[108:109], v[18:19] op_sel_hi:[1,0]
	v_pk_mul_f32 v[106:107], v[106:107], v[18:19] op_sel_hi:[1,0]
	v_pk_mul_f32 v[100:101], v[100:101], v[18:19] op_sel_hi:[1,0]
	v_pk_mul_f32 v[98:99], v[98:99], v[18:19] op_sel_hi:[1,0]
	v_pk_mul_f32 v[92:93], v[92:93], v[18:19] op_sel_hi:[1,0]
	v_pk_mul_f32 v[90:91], v[90:91], v[18:19] op_sel_hi:[1,0]
	v_pk_mul_f32 v[84:85], v[84:85], v[18:19] op_sel_hi:[1,0]
	v_pk_mul_f32 v[82:83], v[82:83], v[18:19] op_sel_hi:[1,0]
	v_pk_mul_f32 v[72:73], v[72:73], v[18:19] op_sel_hi:[1,0]
	v_pk_mul_f32 v[70:71], v[70:71], v[18:19] op_sel_hi:[1,0]
	v_pk_mul_f32 v[68:69], v[68:69], v[18:19] op_sel_hi:[1,0]
	v_pk_mul_f32 v[66:67], v[66:67], v[18:19] op_sel_hi:[1,0]
	v_pk_mul_f32 v[56:57], v[56:57], v[18:19] op_sel_hi:[1,0]
	v_pk_mul_f32 v[54:55], v[54:55], v[18:19] op_sel_hi:[1,0]

; DI unsigned pk2(float lo, float hi) { const f32x2 v = {lo, hi}; const bf16x2_t b = __builtin_convertvector(v, bf16x2_t); return __builtin_bit_cast(unsigned, b); }
; #define MFMA16(a, b, c) __builtin_amdgcn_mfma_f32_16x16x32_bf16((a), (b), (c), 0, 0, 0)
; #define AT_VLD(dst, db_) { _Pragma("unroll") for (int s2 = 0; s2 < 2; ++s2) { const LAS bf16* vp = Vs + ((db_) * 16 + lc) * 72 + 32 * s2 + 4 * g4; \
;                     const u32x2 v0 = *(const LAS u32x2*)vp, v1 = *(const LAS u32x2*)(vp + 16); const u32x4 vw = (u32x4){v0.x, v0.y, v1.x, v1.y}; dst[s2] = __builtin_bit_cast(bf16x8, vw); } }
; DI void u_attn2(Frame& F, int h, int qb, int sp, int ntile) {
;     ...
;                 for (int s2 = 0; s2 < 2; ++s2) { u32x4 pw; pw.x = pk2(p[8 * s2], p[8 * s2 + 1]); pw.y = pk2(p[8 * s2 + 2], p[8 * s2 + 3]); pw.z = pk2(p[8 * s2 + 4], p[8 * s2 + 5]); pw.w = pk2(p[8 * s2 + 6], p[8 * s2 + 7]); pf[qq][s2] = __builtin_bit_cast(bf16x8, pw); }
;             }
;             {
;                 bf16x8 vfr[2][2];
;     ...
;                 AT_VLD(vfr[0], 0)
; #pragma unroll
;                 for (int db = 0; db < 8; ++db) {
;                     if (db < 7) AT_VLD(vfr[(db + 1) & 1], db + 1)
; #pragma unroll
;                     for (int s2 = 0; s2 < 2; ++s2)
; #pragma unroll
;                         for (int qq = 0; qq < 2; ++qq) o[db][qq] = MFMA16(vfr[db & 1][s2], pf[qq][s2], o[db][qq]);
;                 }
;     ...
;             }
.Latt_r1_B:
	v_cvt_pk_bf16_f32 v142, v142, v143
	v_cvt_pk_bf16_f32 v143, v144, v145
	v_cvt_pk_bf16_f32 v145, v140, v141
	v_cvt_pk_bf16_f32 v198, v192, v194
	v_cvt_pk_bf16_f32 v200, v193, v195
	v_cvt_pk_bf16_f32 v192, v211, v212
	v_cvt_pk_bf16_f32 v193, v213, v214
	v_cvt_pk_bf16_f32 v212, v146, v147
	v_cvt_pk_bf16_f32 v213, v148, v149
	v_cvt_pk_bf16_f32 v199, v164, v191
	v_cvt_pk_bf16_f32 v201, v203, v210
	v_cvt_pk_bf16_f32 v210, v162, v218
	v_cvt_pk_bf16_f32 v211, v150, v151
	v_cvt_pk_bf16_f32 v194, v215, v217
	v_cvt_pk_bf16_f32 v195, v156, v157
	v_cvt_pk_bf16_f32 v144, v152, v153
	v_add_f32_e32 v138, v138, v139
	v_fmac_f32_e32 v138, v163, v20
	v_add_f32_e32 v20, v154, v155
	v_fmac_f32_e32 v20, v165, v18
	v_mov_b32_e32 v165, v20
	v_mov_b32_e32 v163, v138
	v_mov_b32_e32 v164, v21
	v_mov_b32_e32 v162, v216
	v_add_u32_e32 v140, 0x6000, v189
	ds_read2_b64 v[146:149], v140 offset0:128 offset1:132
	ds_read2_b64 v[244:247], v140 offset0:136 offset1:140
	v_add_u32_e32 v219, 0x6000, v188
	v_add_u32_e32 v140, 0x6800, v189
	ds_read2_b64 v[220:223], v219 offset0:128 offset1:132
	ds_read2_b64 v[224:227], v219 offset0:136 offset1:140
	s_waitcnt lgkmcnt(3)
	v_mfma_f32_16x16x32_bf16 v[106:109], v[146:149], v[198:201], v[106:109]
	v_mfma_f32_16x16x32_bf16 v[102:105], v[146:149], v[210:213], v[102:105]
	ds_read2_b64 v[146:149], v140 offset0:160 offset1:164
	s_waitcnt lgkmcnt(3)
	v_mfma_f32_16x16x32_bf16 v[106:109], v[244:247], v[192:195], v[106:109]
	v_mfma_f32_16x16x32_bf16 v[102:105], v[244:247], v[142:145], v[102:105]
	ds_read2_b64 v[244:247], v140 offset0:168 offset1:172
	v_add_u32_e32 v140, 0x7000, v189
	s_waitcnt lgkmcnt(1)
	v_mfma_f32_16x16x32_bf16 v[98:101], v[146:149], v[198:201], v[98:101]
	v_mfma_f32_16x16x32_bf16 v[94:97], v[146:149], v[210:213], v[94:97]
	ds_read2_b64 v[146:149], v140 offset0:192 offset1:196
	s_waitcnt lgkmcnt(1)
	v_mfma_f32_16x16x32_bf16 v[98:101], v[244:247], v[192:195], v[98:101]
	v_mfma_f32_16x16x32_bf16 v[94:97], v[244:247], v[142:145], v[94:97]
	ds_read2_b64 v[244:247], v140 offset0:200 offset1:204
	v_add_u32_e32 v140, 0x8800, v190
	s_waitcnt lgkmcnt(1)
	v_mfma_f32_16x16x32_bf16 v[90:93], v[146:149], v[198:201], v[90:93]
	v_mfma_f32_16x16x32_bf16 v[86:89], v[146:149], v[210:213], v[86:89]
	ds_read2_b64 v[146:149], v140 offset1:4
	s_waitcnt lgkmcnt(1)
	v_mfma_f32_16x16x32_bf16 v[90:93], v[244:247], v[192:195], v[90:93]
	v_mfma_f32_16x16x32_bf16 v[86:89], v[244:247], v[142:145], v[86:89]
	ds_read2_b64 v[244:247], v140 offset0:8 offset1:12
	v_add_u32_e32 v140, 0x9000, v190
	s_waitcnt lgkmcnt(1)
	v_mfma_f32_16x16x32_bf16 v[82:85], v[146:149], v[198:201], v[82:85]
	v_mfma_f32_16x16x32_bf16 v[78:81], v[146:149], v[210:213], v[78:81]
	ds_read2_b64 v[146:149], v140 offset0:32 offset1:36
	s_waitcnt lgkmcnt(1)
	v_mfma_f32_16x16x32_bf16 v[82:85], v[244:247], v[192:195], v[82:85]
	v_mfma_f32_16x16x32_bf16 v[78:81], v[244:247], v[142:145], v[78:81]
	ds_read2_b64 v[244:247], v140 offset0:40 offset1:44
	v_add_u32_e32 v140, 0x9800, v190
	s_waitcnt lgkmcnt(1)
	v_mfma_f32_16x16x32_bf16 v[70:73], v[146:149], v[198:201], v[70:73]
	v_mfma_f32_16x16x32_bf16 v[74:77], v[146:149], v[210:213], v[74:77]
	ds_read2_b64 v[146:149], v140 offset0:64 offset1:68
	s_waitcnt lgkmcnt(1)
	v_mfma_f32_16x16x32_bf16 v[70:73], v[244:247], v[192:195], v[70:73]
	v_mfma_f32_16x16x32_bf16 v[74:77], v[244:247], v[142:145], v[74:77]
	ds_read2_b64 v[244:247], v140 offset0:72 offset1:76
	v_add_u32_e32 v140, 0xa000, v190
	s_waitcnt lgkmcnt(1)
	v_mfma_f32_16x16x32_bf16 v[66:69], v[146:149], v[198:201], v[66:69]
	v_mfma_f32_16x16x32_bf16 v[58:61], v[146:149], v[210:213], v[58:61]
	ds_read2_b64 v[146:149], v140 offset0:96 offset1:100
	ds_read2_b64 v[150:153], v140 offset0:104 offset1:108
	s_waitcnt lgkmcnt(2)
	v_mfma_f32_16x16x32_bf16 v[66:69], v[244:247], v[192:195], v[66:69]
	v_mfma_f32_16x16x32_bf16 v[58:61], v[244:247], v[142:145], v[58:61]
	v_mfma_f32_16x16x32_bf16 v[134:137], v[220:223], v[198:201], v[134:137]
	v_mfma_f32_16x16x32_bf16 v[118:121], v[220:223], v[210:213], v[118:121]
	s_waitcnt lgkmcnt(1)
	v_mfma_f32_16x16x32_bf16 v[54:57], v[146:149], v[198:201], v[54:57]
	v_mfma_f32_16x16x32_bf16 v[62:65], v[146:149], v[210:213], v[62:65]
	v_mfma_f32_16x16x32_bf16 v[134:137], v[224:227], v[192:195], v[134:137]
	v_mfma_f32_16x16x32_bf16 v[118:121], v[224:227], v[142:145], v[118:121]
	s_waitcnt lgkmcnt(0)
	v_mfma_f32_16x16x32_bf16 v[54:57], v[150:153], v[192:195], v[54:57]
	v_mfma_f32_16x16x32_bf16 v[62:65], v[150:153], v[142:145], v[62:65]
; #define MFMA16(a, b, c) __builtin_amdgcn_mfma_f32_16x16x32_bf16((a), (b), (c), 0, 0, 0)
; DI void u_attn2(Frame& F, int h, int qb, int sp, int ntile) {
;     ...
;         if (kt <= cw) {
;             f32x4 s[4][2];
; #pragma unroll
;             for (int kb = 0; kb < 4; ++kb)
; #pragma unroll
;                 for (int qq = 0; qq < 2; ++qq) s[kb][qq] = (f32x4){0.f, 0.f, 0.f, 0.f};
;             {
;                 bf16x8 kfr[2][4];
; #pragma unroll
;                 for (int kb = 0; kb < 4; ++kb) kfr[0][kb] = ldfrag(Ks, 200, kb * 16, 0, lane);
; #pragma unroll
;                 for (int ks = 0; ks < 6; ++ks) {
;                     if (ks < 5) {
; #pragma unroll
;                         for (int kb = 0; kb < 4; ++kb) kfr[(ks + 1) & 1][kb] = ldfrag(Ks, 200, kb * 16, (ks + 1) * 32, lane); }
; #pragma unroll
;                     for (int kb = 0; kb < 4; ++kb)
; #pragma unroll
;                         for (int qq = 0; qq < 2; ++qq) s[kb][qq] = MFMA16(kfr[ks & 1][kb], qf[qq][ks], s[kb][qq]);
;                 }
;             }
.Latt_B_qk:
	v_cmp_lt_i32_e32 vcc, s46, v179
	s_cbranch_vccz .LBB0_2236
	v_add_u32_e32 v18, s46, v181
	v_cmp_le_i32_e32 vcc, v18, v180
	s_cbranch_vccz .LBB0_2236
	ds_read_b128 v[138:141], v187
	ds_read_b128 v[142:145], v187 offset:6400
	ds_read_b128 v[146:149], v187 offset:12800
	ds_read_b128 v[150:153], v187 offset:19200
	ds_read_b128 v[154:157], v187 offset:64
	ds_read_b128 v[192:195], v187 offset:6464
	ds_read_b128 v[210:213], v187 offset:12864
	ds_read_b128 v[214:217], v187 offset:19264
	s_waitcnt lgkmcnt(7)
	v_mfma_f32_16x16x32_bf16 v[218:221], v[138:141], v[2:5], 0
	ds_read_b128 v[244:247], v187 offset:128
	ds_read_b128 v[248:251], v187 offset:6528
	ds_read_b128 v[198:201], v187 offset:12928
	ds_read_b128 v[230:233], v187 offset:19328
	v_mov_b32_e32 v234, 0x42800000
	v_mfma_f32_16x16x32_bf16 v[138:141], v[138:141], v[30:33], 0
	s_waitcnt lgkmcnt(10)
	v_mfma_f32_16x16x32_bf16 v[222:225], v[142:145], v[2:5], 0
	v_mfma_f32_16x16x32_bf16 v[142:145], v[142:145], v[30:33], 0
	s_waitcnt lgkmcnt(9)
	v_mfma_f32_16x16x32_bf16 v[226:229], v[146:149], v[2:5], 0
	s_waitcnt lgkmcnt(7)
	v_mfma_f32_16x16x32_bf16 v[218:221], v[154:157], v[6:9], v[218:221]
	v_mfma_f32_16x16x32_bf16 v[146:149], v[146:149], v[30:33], 0
	v_mfma_f32_16x16x32_bf16 v[240:243], v[150:153], v[2:5], 0
	v_mfma_f32_16x16x32_bf16 v[150:153], v[150:153], v[30:33], 0
	v_mfma_f32_16x16x32_bf16 v[138:141], v[154:157], v[34:37], v[138:141]
	s_waitcnt lgkmcnt(6)
	v_mfma_f32_16x16x32_bf16 v[154:157], v[192:195], v[6:9], v[222:225]
	v_mfma_f32_16x16x32_bf16 v[142:145], v[192:195], v[34:37], v[142:145]
	s_waitcnt lgkmcnt(5)
	v_mfma_f32_16x16x32_bf16 v[192:195], v[210:213], v[6:9], v[226:229]
	s_waitcnt lgkmcnt(3)
	v_mfma_f32_16x16x32_bf16 v[218:221], v[244:247], v[10:13], v[218:221]
	v_mfma_f32_16x16x32_bf16 v[146:149], v[210:213], v[34:37], v[146:149]
	v_mfma_f32_16x16x32_bf16 v[210:213], v[214:217], v[6:9], v[240:243]
	v_mfma_f32_16x16x32_bf16 v[150:153], v[214:217], v[34:37], v[150:153]
	ds_read_b128 v[214:217], v187 offset:192
	ds_read_b128 v[222:225], v187 offset:6592
	ds_read_b128 v[226:229], v187 offset:12992
	ds_read_b128 v[240:243], v187 offset:19392
	v_mfma_f32_16x16x32_bf16 v[138:141], v[244:247], v[38:41], v[138:141]
	s_waitcnt lgkmcnt(6)
	v_mfma_f32_16x16x32_bf16 v[154:157], v[248:251], v[10:13], v[154:157]
	v_mfma_f32_16x16x32_bf16 v[142:145], v[248:251], v[38:41], v[142:145]
	s_waitcnt lgkmcnt(5)
	v_mfma_f32_16x16x32_bf16 v[192:195], v[198:201], v[10:13], v[192:195]
	s_waitcnt lgkmcnt(3)
	v_mfma_f32_16x16x32_bf16 v[218:221], v[214:217], v[14:17], v[218:221]
	v_mfma_f32_16x16x32_bf16 v[146:149], v[198:201], v[38:41], v[146:149]
	v_mfma_f32_16x16x32_bf16 v[198:201], v[230:233], v[10:13], v[210:213]
	v_mfma_f32_16x16x32_bf16 v[150:153], v[230:233], v[38:41], v[150:153]
	s_nop 1
	ds_read_b128 v[210:213], v187 offset:256
	ds_read_b128 v[230:233], v187 offset:6656
	ds_read_b128 v[244:247], v187 offset:13056
	ds_read_b128 v[248:251], v187 offset:19456
	v_mfma_f32_16x16x32_bf16 v[138:141], v[214:217], v[42:45], v[138:141]
	s_waitcnt lgkmcnt(6)
	v_mfma_f32_16x16x32_bf16 v[154:157], v[222:225], v[14:17], v[154:157]
	v_mfma_f32_16x16x32_bf16 v[142:145], v[222:225], v[42:45], v[142:145]
	s_waitcnt lgkmcnt(5)
	v_mfma_f32_16x16x32_bf16 v[192:195], v[226:229], v[14:17], v[192:195]
	s_waitcnt lgkmcnt(3)
	v_mfma_f32_16x16x32_bf16 v[218:221], v[210:213], v[22:25], v[218:221]
	v_mfma_f32_16x16x32_bf16 v[198:201], v[240:243], v[14:17], v[198:201]
	v_mfma_f32_16x16x32_bf16 v[150:153], v[240:243], v[42:45], v[150:153]
	v_mfma_f32_16x16x32_bf16 v[138:141], v[210:213], v[46:49], v[138:141]
	s_waitcnt lgkmcnt(2)
	v_mfma_f32_16x16x32_bf16 v[154:157], v[230:233], v[22:25], v[154:157]
	v_mfma_f32_16x16x32_bf16 v[146:149], v[226:229], v[42:45], v[146:149]
	ds_read_b128 v[214:217], v187 offset:320
	ds_read_b128 v[222:225], v187 offset:6720
	ds_read_b128 v[226:229], v187 offset:13120
	ds_read_b128 v[240:243], v187 offset:19520
	v_mfma_f32_16x16x32_bf16 v[142:145], v[230:233], v[46:49], v[142:145]
	s_waitcnt lgkmcnt(5)
	v_mfma_f32_16x16x32_bf16 v[192:195], v[244:247], v[22:25], v[192:195]
	s_waitcnt lgkmcnt(3)
	v_mfma_f32_16x16x32_bf16 v[218:221], v[214:217], v[26:29], v[218:221]
	v_mfma_f32_16x16x32_bf16 v[198:201], v[248:251], v[22:25], v[198:201]
	v_mfma_f32_16x16x32_bf16 v[230:233], v[248:251], v[46:49], v[150:153]
	v_mfma_f32_16x16x32_bf16 v[150:153], v[214:217], v[50:53], v[138:141]
	s_waitcnt lgkmcnt(2)
	v_mfma_f32_16x16x32_bf16 v[214:217], v[222:225], v[26:29], v[154:157]
	v_mfma_f32_16x16x32_bf16 v[210:213], v[244:247], v[46:49], v[146:149]
	v_mfma_f32_16x16x32_bf16 v[146:149], v[222:225], v[50:53], v[142:145]
	s_waitcnt lgkmcnt(1)
	v_mfma_f32_16x16x32_bf16 v[222:225], v[226:229], v[26:29], v[192:195]
	s_waitcnt lgkmcnt(0)
	v_mfma_f32_16x16x32_bf16 v[154:157], v[240:243], v[26:29], v[198:201]
	v_mfma_f32_16x16x32_bf16 v[138:141], v[240:243], v[50:53], v[230:233]
	s_nop 1
	v_mfma_f32_16x16x32_bf16 v[142:145], v[226:229], v[50:53], v[210:213]
	s_branch .LBB0_2236
